# S5 scans: complex recurrence as 2 packed FMAs per step, C-MFMA operand reads issued together; LRU scan1 init loads batched
# speedup vs baseline: 1.0630x; 1.0062x over previous
; #define LAS __attribute__((address_space(3)))
; #define LDS_WAIT() asm volatile("s_waitcnt lgkmcnt(0)" ::: "memory")
; __device__ __forceinline__ u32x2 s5_load_u(const bf16_t* U, int t0, int g, int lane) { if (t0 > T - 16) t0 = T - 16; return *(const u32x2*)(U + (size_t)(t0 + (lane >> 2)) * D + g * 16 + (lane & 3) * 4); }
; __device__ __forceinline__ f32x4 s5_u_f32(const u32x2 w) { return (f32x4){bflo(w.x), bfhi(w.x), bflo(w.y), bfhi(w.y)}; }
; __device__ __forceinline__ void s5_bu_tile(const S5Item& L, const f32x4 ucur, LAS unsigned char* wlds, int lane) {
;     LAS float* ut = (LAS float*)(wlds + S5_OFF_U);
;     *(LAS f32x4*)(ut + (lane >> 2) * 16 + (lane & 3) * 4) = ucur;
;     LDS_WAIT(); __builtin_amdgcn_wave_barrier();
;     const LAS f32x4* up = (const LAS f32x4*)(ut + (lane & 15) * 16 + ((lane >> 4) & 1) * 8);
;     const f32x4 u0 = up[0], u1 = up[1];
;     u32x4 w; w.x = cvt_pk_bf16(u0[0], u0[1]); w.y = cvt_pk_bf16(u0[2], u0[3]); w.z = cvt_pk_bf16(u1[0], u1[1]); w.w = cvt_pk_bf16(u1[2], u1[3]);
;     const bf16x8 uf = __builtin_bit_cast(bf16x8, w);
; #pragma unroll
;     for (int f = 0; f < 8; ++f) {
;         f32x4 d = (f32x4){0.f, 0.f, 0.f, 0.f};
;         d = __builtin_amdgcn_mfma_f32_16x16x32_bf16(L.bf[f], uf, d, 0, 0, 0);
;         *(LAS f32x4*)(wlds + (lane & 15) * S5_BU_STRIDE + (16 * f + (lane >> 4) * 4) * 4) = d;
;     }
;     LDS_WAIT(); __builtin_amdgcn_wave_barrier();
; __device__ __forceinline__ void s5_scan1(LAS unsigned char* lds, const S5Params& P, const bf16_t* U, float* ES, int bid, int G) {
;     ...
;         for (int t0 = c * S5_L; t0 < (c + 1) * S5_L; t0 += 16) {
;             const f32x4 ucur = s5_u_f32(uq0);
;             uq0 = uq1; uq1 = uq2; uq2 = uq3; uq3 = s5_load_u(U, t0 + 64, g, lane);
;             s5_bu_tile(L, ucur, wlds, lane);
; #pragma unroll
;             for (int i = 0; i < 16; ++i) { const f32x2 bu = *(const LAS f32x2*)(wlds + i * S5_BU_STRIDE + lane * 8);
;                 const float nre = L.abr * sre - L.abi * sim + bu[0], nim = L.abr * sim + L.abi * sre + bu[1]; sre = nre; sim = nim; }
;             LDS_WAIT(); __builtin_amdgcn_wave_barrier();
;         }
.LBB0_1179:
	s_min_i32 s1, s8, 0x1fb0
	v_add_u32_e32 v44, s1, v88
	v_ashrrev_i32_e32 v45, 31, v44
	v_lshlrev_b32_e32 v40, 16, v76
	v_and_b32_e32 v41, 0xffff0000, v76
	v_lshlrev_b32_e32 v42, 16, v77
	v_and_b32_e32 v43, 0xffff0000, v77
	v_lshlrev_b64 v[44:45], 12, v[44:45]
	v_lshl_add_u64 v[44:45], v[66:67], 0, v[44:45]
	ds_write_b128 v89, v[40:43] offset:12800
	v_mov_b64_e32 v[38:39], v[68:69]
	s_waitcnt vmcnt(0)
	v_mov_b64_e32 v[68:69], v[70:71]
	global_load_dwordx2 v[70:71], v[44:45], off
	s_waitcnt lgkmcnt(0)
	ds_read_b128 v[40:43], v90 offset:12800
	ds_read_b128 v[44:47], v90 offset:12816
	v_add_u32_e32 v61, 0x800, v91
	s_add_i32 s1, s8, 16
	s_cmp_ge_i32 s8, s0
	s_waitcnt lgkmcnt(1)
	v_cvt_pk_bf16_f32 v40, v40, v41
	v_cvt_pk_bf16_f32 v41, v42, v43
	s_waitcnt lgkmcnt(0)
	v_cvt_pk_bf16_f32 v42, v44, v45
	v_cvt_pk_bf16_f32 v43, v46, v47
	s_mov_b32 s8, s1
	s_nop 0
	v_mfma_f32_16x16x32_bf16 v[44:47], v[32:35], v[40:43], 0
	s_nop 7
	ds_write_b128 v51, v[44:47]
	v_mfma_f32_16x16x32_bf16 v[44:47], v[26:29], v[40:43], 0
	s_nop 7
	ds_write_b128 v51, v[44:47] offset:64
	v_mfma_f32_16x16x32_bf16 v[44:47], v[22:25], v[40:43], 0
	s_nop 7
	ds_write_b128 v51, v[44:47] offset:128
	v_mfma_f32_16x16x32_bf16 v[44:47], v[18:21], v[40:43], 0
	s_nop 7
	ds_write_b128 v51, v[44:47] offset:192
	v_mfma_f32_16x16x32_bf16 v[44:47], v[14:17], v[40:43], 0
	s_nop 7
	ds_write_b128 v51, v[44:47] offset:256
	v_mfma_f32_16x16x32_bf16 v[44:47], v[10:13], v[40:43], 0
	s_nop 7
	ds_write_b128 v51, v[44:47] offset:320
	v_mfma_f32_16x16x32_bf16 v[44:47], v[6:9], v[40:43], 0
	v_mfma_f32_16x16x32_bf16 v[40:43], v[2:5], v[40:43], 0
	s_nop 6
	ds_write_b128 v51, v[44:47] offset:384
	ds_write_b128 v51, v[40:43] offset:448
	s_waitcnt lgkmcnt(0)
	ds_read2_b64 v[40:43], v91 offset1:66
	ds_read2_b64 v[44:47], v91 offset0:132 offset1:198
	s_waitcnt lgkmcnt(1)
	v_pk_fma_f32 v[48:49], v[62:63], v[74:75], v[40:41]
	s_nop 0
	v_pk_fma_f32 v[74:75], v[64:65], v[74:75], v[48:49] op_sel:[0,1,0] op_sel_hi:[1,0,1] neg_lo:[1,0,0]
	s_nop 0
	v_pk_fma_f32 v[48:49], v[62:63], v[74:75], v[42:43]
	s_nop 0
	v_pk_fma_f32 v[74:75], v[64:65], v[74:75], v[48:49] op_sel:[0,1,0] op_sel_hi:[1,0,1] neg_lo:[1,0,0]
	s_nop 0
	v_add_u32_e32 v61, 0x800, v91
	ds_read2_b64 v[40:43], v61 offset0:8 offset1:74
	s_waitcnt lgkmcnt(1)
	v_pk_fma_f32 v[48:49], v[62:63], v[74:75], v[44:45]
	s_nop 0
	v_pk_fma_f32 v[74:75], v[64:65], v[74:75], v[48:49] op_sel:[0,1,0] op_sel_hi:[1,0,1] neg_lo:[1,0,0]
	s_nop 0
	v_pk_fma_f32 v[48:49], v[62:63], v[74:75], v[46:47]
	s_nop 0
	v_pk_fma_f32 v[74:75], v[64:65], v[74:75], v[48:49] op_sel:[0,1,0] op_sel_hi:[1,0,1] neg_lo:[1,0,0]
	s_nop 0
	v_add_u32_e32 v61, 0x800, v91
	ds_read2_b64 v[44:47], v61 offset0:140 offset1:206
	s_waitcnt lgkmcnt(1)
	v_pk_fma_f32 v[48:49], v[62:63], v[74:75], v[40:41]
	s_nop 0
	v_pk_fma_f32 v[74:75], v[64:65], v[74:75], v[48:49] op_sel:[0,1,0] op_sel_hi:[1,0,1] neg_lo:[1,0,0]
	s_nop 0
	v_pk_fma_f32 v[48:49], v[62:63], v[74:75], v[42:43]
	s_nop 0
	v_pk_fma_f32 v[74:75], v[64:65], v[74:75], v[48:49] op_sel:[0,1,0] op_sel_hi:[1,0,1] neg_lo:[1,0,0]
	s_nop 0
	v_add_u32_e32 v61, 0x1000, v91
	ds_read2_b64 v[40:43], v61 offset0:16 offset1:82
	s_waitcnt lgkmcnt(1)
	v_pk_fma_f32 v[48:49], v[62:63], v[74:75], v[44:45]
	s_nop 0
	v_pk_fma_f32 v[74:75], v[64:65], v[74:75], v[48:49] op_sel:[0,1,0] op_sel_hi:[1,0,1] neg_lo:[1,0,0]
	s_nop 0
	v_pk_fma_f32 v[48:49], v[62:63], v[74:75], v[46:47]
	s_nop 0
	v_pk_fma_f32 v[74:75], v[64:65], v[74:75], v[48:49] op_sel:[0,1,0] op_sel_hi:[1,0,1] neg_lo:[1,0,0]
	s_nop 0
	v_add_u32_e32 v61, 0x1000, v91
	ds_read2_b64 v[44:47], v61 offset0:148 offset1:214
	s_waitcnt lgkmcnt(1)
	v_pk_fma_f32 v[48:49], v[62:63], v[74:75], v[40:41]
	s_nop 0
	v_pk_fma_f32 v[74:75], v[64:65], v[74:75], v[48:49] op_sel:[0,1,0] op_sel_hi:[1,0,1] neg_lo:[1,0,0]
	s_nop 0
	v_pk_fma_f32 v[48:49], v[62:63], v[74:75], v[42:43]
	s_nop 0
	v_pk_fma_f32 v[74:75], v[64:65], v[74:75], v[48:49] op_sel:[0,1,0] op_sel_hi:[1,0,1] neg_lo:[1,0,0]
	s_nop 0
	v_add_u32_e32 v61, 0x1800, v91
	ds_read2_b64 v[40:43], v61 offset0:24 offset1:90
	s_waitcnt lgkmcnt(1)
	v_pk_fma_f32 v[48:49], v[62:63], v[74:75], v[44:45]
	s_nop 0
	v_pk_fma_f32 v[74:75], v[64:65], v[74:75], v[48:49] op_sel:[0,1,0] op_sel_hi:[1,0,1] neg_lo:[1,0,0]
	s_nop 0
	v_pk_fma_f32 v[48:49], v[62:63], v[74:75], v[46:47]
	s_nop 0
	v_pk_fma_f32 v[74:75], v[64:65], v[74:75], v[48:49] op_sel:[0,1,0] op_sel_hi:[1,0,1] neg_lo:[1,0,0]
	s_nop 0
	v_add_u32_e32 v61, 0x1800, v91
	ds_read2_b64 v[44:47], v61 offset0:156 offset1:222
	s_waitcnt lgkmcnt(1)
	v_pk_fma_f32 v[48:49], v[62:63], v[74:75], v[40:41]
	s_nop 0
	v_pk_fma_f32 v[74:75], v[64:65], v[74:75], v[48:49] op_sel:[0,1,0] op_sel_hi:[1,0,1] neg_lo:[1,0,0]
	s_nop 0
	v_pk_fma_f32 v[48:49], v[62:63], v[74:75], v[42:43]
	s_nop 0
	v_pk_fma_f32 v[74:75], v[64:65], v[74:75], v[48:49] op_sel:[0,1,0] op_sel_hi:[1,0,1] neg_lo:[1,0,0]
	s_nop 0
	s_waitcnt lgkmcnt(0)
	v_pk_fma_f32 v[48:49], v[62:63], v[74:75], v[44:45]
	s_nop 0
	v_pk_fma_f32 v[74:75], v[64:65], v[74:75], v[48:49] op_sel:[0,1,0] op_sel_hi:[1,0,1] neg_lo:[1,0,0]
	s_nop 0
	v_pk_fma_f32 v[48:49], v[62:63], v[74:75], v[46:47]
	s_nop 0
	v_pk_fma_f32 v[74:75], v[64:65], v[74:75], v[48:49] op_sel:[0,1,0] op_sel_hi:[1,0,1] neg_lo:[1,0,0]
	s_nop 0
	s_waitcnt lgkmcnt(0)
	v_mov_b64_e32 v[76:77], v[72:73]
	v_mov_b64_e32 v[72:73], v[38:39]
	s_cbranch_scc0 .LBB0_1179
	s_add_i32 s0, s42, s10
	s_ashr_i32 s1, s0, 31
	s_lshl_b64 s[0:1], s[0:1], 9
	s_add_i32 s44, s44, s82
	v_lshl_add_u64 v[2:3], v[54:55], 0, s[0:1]
	s_cmpk_gt_i32 s44, 0xfff
	global_store_dwordx2 v[2:3], v[74:75], off
	s_cbranch_scc0 .LBB0_1170

; #define LAS __attribute__((address_space(3)))
; #define LDS_WAIT() asm volatile("s_waitcnt lgkmcnt(0)" ::: "memory")
; __device__ __forceinline__ u32x2 s5_load_u(const bf16_t* U, int t0, int g, int lane) { if (t0 > T - 16) t0 = T - 16; return *(const u32x2*)(U + (size_t)(t0 + (lane >> 2)) * D + g * 16 + (lane & 3) * 4); }
; __device__ __forceinline__ f32x4 s5_u_f32(const u32x2 w) { return (f32x4){bflo(w.x), bfhi(w.x), bflo(w.y), bfhi(w.y)}; }
; __device__ __forceinline__ void s5_bu_tile(const S5Item& L, const f32x4 ucur, LAS unsigned char* wlds, int lane) {
;     LAS float* ut = (LAS float*)(wlds + S5_OFF_U);
;     *(LAS f32x4*)(ut + (lane >> 2) * 16 + (lane & 3) * 4) = ucur;
;     LDS_WAIT(); __builtin_amdgcn_wave_barrier();
;     const LAS f32x4* up = (const LAS f32x4*)(ut + (lane & 15) * 16 + ((lane >> 4) & 1) * 8);
;     const f32x4 u0 = up[0], u1 = up[1];
;     u32x4 w; w.x = cvt_pk_bf16(u0[0], u0[1]); w.y = cvt_pk_bf16(u0[2], u0[3]); w.z = cvt_pk_bf16(u1[0], u1[1]); w.w = cvt_pk_bf16(u1[2], u1[3]);
;     const bf16x8 uf = __builtin_bit_cast(bf16x8, w);
; #pragma unroll
;     for (int f = 0; f < 8; ++f) {
;         f32x4 d = (f32x4){0.f, 0.f, 0.f, 0.f};
;         d = __builtin_amdgcn_mfma_f32_16x16x32_bf16(L.bf[f], uf, d, 0, 0, 0);
;         *(LAS f32x4*)(wlds + (lane & 15) * S5_BU_STRIDE + (16 * f + (lane >> 4) * 4) * 4) = d;
;     }
;     LDS_WAIT(); __builtin_amdgcn_wave_barrier();
; __device__ __forceinline__ void s5_scan2(LAS unsigned char* lds, const S5Params& P, const bf16_t* U, const float* ES, bf16_t* Gb, int bid, int G) {
;     ...
;         for (int t0 = c * S5_L; t0 < (c + 1) * S5_L; t0 += 16) {
;             const f32x4 ucur = s5_u_f32(uq0);
;             uq0 = uq1; uq1 = uq2; uq2 = uq3; uq3 = s5_load_u(U, t0 + 64, g, lane);
;             s5_bu_tile(L, ucur, wlds, lane);
; #pragma unroll
;             for (int i = 0; i < 16; ++i) { const f32x2 bu = *(const LAS f32x2*)(wlds + i * S5_BU_STRIDE + lane * 8);
;                 const float nre = L.abr * sre - L.abi * sim + bu[0], nim = L.abr * sim + L.abi * sre + bu[1]; sre = nre; sim = nim;
;                 *(LAS unsigned*)(sb + i * S5_SB_STRIDE + lane * 4) = cvt_pk_bf16(sre, sim); }
;             LDS_WAIT(); __builtin_amdgcn_wave_barrier();
.LBB0_1251:
	s_min_i32 s3, s0, 0x1fb0
	s_waitcnt vmcnt(2)
	v_mov_b64_e32 v[64:65], v[60:61]
	v_mov_b64_e32 v[60:61], v[56:57]
	s_waitcnt vmcnt(1)
	v_mov_b64_e32 v[56:57], v[62:63]
	v_add_u32_e32 v62, s3, v193
	v_ashrrev_i32_e32 v63, 31, v62
	s_waitcnt vmcnt(1)
	v_lshlrev_b32_e32 v68, 16, v66
	v_and_b32_e32 v69, 0xffff0000, v66
	v_lshlrev_b32_e32 v70, 16, v67
	v_and_b32_e32 v71, 0xffff0000, v67
	v_lshlrev_b64 v[62:63], 12, v[62:63]
	v_lshl_add_u64 v[62:63], v[54:55], 0, v[62:63]
	ds_write_b128 v194, v[68:71] offset:12800
	global_load_dwordx2 v[62:63], v[62:63], off
	s_waitcnt lgkmcnt(0)
	ds_read_b128 v[66:69], v196 offset:12800
	ds_read_b128 v[70:73], v196 offset:12816
	v_add_u32_e32 v1, s33, v192
	v_add_u32_e32 v76, 0x800, v200
	s_add_i32 s3, s0, 16
	s_waitcnt lgkmcnt(1)
	v_cvt_pk_bf16_f32 v66, v66, v67
	v_cvt_pk_bf16_f32 v67, v68, v69
	s_waitcnt lgkmcnt(0)
	v_cvt_pk_bf16_f32 v68, v70, v71
	v_cvt_pk_bf16_f32 v69, v72, v73
	s_cmp_ge_i32 s0, s1
	s_nop 0
	v_mfma_f32_16x16x32_bf16 v[70:73], v[2:5], v[66:69], 0
	s_nop 7
	ds_write_b128 v197, v[70:73]
	v_mfma_f32_16x16x32_bf16 v[70:73], v[6:9], v[66:69], 0
	s_nop 7
	ds_write_b128 v197, v[70:73] offset:64
	v_mfma_f32_16x16x32_bf16 v[70:73], v[10:13], v[66:69], 0
	s_nop 7
	ds_write_b128 v197, v[70:73] offset:128
	v_mfma_f32_16x16x32_bf16 v[70:73], v[14:17], v[66:69], 0
	s_nop 7
	ds_write_b128 v197, v[70:73] offset:192
	v_mfma_f32_16x16x32_bf16 v[70:73], v[18:21], v[66:69], 0
	s_nop 7
	ds_write_b128 v197, v[70:73] offset:256
	v_mfma_f32_16x16x32_bf16 v[70:73], v[22:25], v[66:69], 0
	s_nop 7
	ds_write_b128 v197, v[70:73] offset:320
	v_mfma_f32_16x16x32_bf16 v[70:73], v[26:29], v[66:69], 0
	v_mfma_f32_16x16x32_bf16 v[66:69], v[34:37], v[66:69], 0
	s_nop 6
	ds_write_b128 v197, v[70:73] offset:384
	ds_write_b128 v197, v[66:69] offset:448
	s_waitcnt lgkmcnt(0)
	ds_read2_b64 v[66:69], v200 offset1:66
	ds_read2_b64 v[70:73], v200 offset0:132 offset1:198
	s_waitcnt lgkmcnt(1)
	v_pk_fma_f32 v[76:77], v[166:167], v[168:169], v[66:67]
	s_nop 0
	v_pk_fma_f32 v[168:169], v[164:165], v[168:169], v[76:77] op_sel:[0,1,0] op_sel_hi:[1,0,1] neg_lo:[1,0,0]
	s_nop 0
	v_cvt_pk_bf16_f32 v75, v168, v169
	v_pk_fma_f32 v[76:77], v[166:167], v[168:169], v[68:69]
	s_nop 0
	v_pk_fma_f32 v[168:169], v[164:165], v[168:169], v[76:77] op_sel:[0,1,0] op_sel_hi:[1,0,1] neg_lo:[1,0,0]
	s_nop 0
	v_cvt_pk_bf16_f32 v79, v168, v169
	v_add_u32_e32 v74, 0x2000, v1
	ds_write2_b32 v74, v75, v79 offset0:64 offset1:132
	v_add_u32_e32 v78, 0x800, v200
	ds_read2_b64 v[66:69], v78 offset0:8 offset1:74
	s_waitcnt lgkmcnt(2)
	v_pk_fma_f32 v[76:77], v[166:167], v[168:169], v[70:71]
	s_nop 0
	v_pk_fma_f32 v[168:169], v[164:165], v[168:169], v[76:77] op_sel:[0,1,0] op_sel_hi:[1,0,1] neg_lo:[1,0,0]
	s_nop 0
	v_cvt_pk_bf16_f32 v75, v168, v169
	v_pk_fma_f32 v[76:77], v[166:167], v[168:169], v[72:73]
	s_nop 0
	v_pk_fma_f32 v[168:169], v[164:165], v[168:169], v[76:77] op_sel:[0,1,0] op_sel_hi:[1,0,1] neg_lo:[1,0,0]
	s_nop 0
	v_cvt_pk_bf16_f32 v79, v168, v169
	v_add_u32_e32 v74, 0x2200, v1
	ds_write2_b32 v74, v75, v79 offset0:72 offset1:140
	v_add_u32_e32 v78, 0x800, v200
	ds_read2_b64 v[70:73], v78 offset0:140 offset1:206
	s_waitcnt lgkmcnt(2)
	v_pk_fma_f32 v[76:77], v[166:167], v[168:169], v[66:67]
	s_nop 0
	v_pk_fma_f32 v[168:169], v[164:165], v[168:169], v[76:77] op_sel:[0,1,0] op_sel_hi:[1,0,1] neg_lo:[1,0,0]
	s_nop 0
	v_cvt_pk_bf16_f32 v75, v168, v169
	v_pk_fma_f32 v[76:77], v[166:167], v[168:169], v[68:69]
	s_nop 0
	v_pk_fma_f32 v[168:169], v[164:165], v[168:169], v[76:77] op_sel:[0,1,0] op_sel_hi:[1,0,1] neg_lo:[1,0,0]
	s_nop 0
	v_cvt_pk_bf16_f32 v79, v168, v169
	v_add_u32_e32 v74, 0x2400, v1
	ds_write2_b32 v74, v75, v79 offset0:80 offset1:148
	v_add_u32_e32 v78, 0x1000, v200
	ds_read2_b64 v[66:69], v78 offset0:16 offset1:82
	s_waitcnt lgkmcnt(2)
	v_pk_fma_f32 v[76:77], v[166:167], v[168:169], v[70:71]
	s_nop 0
	v_pk_fma_f32 v[168:169], v[164:165], v[168:169], v[76:77] op_sel:[0,1,0] op_sel_hi:[1,0,1] neg_lo:[1,0,0]
	s_nop 0
	v_cvt_pk_bf16_f32 v75, v168, v169
	v_pk_fma_f32 v[76:77], v[166:167], v[168:169], v[72:73]
	s_nop 0
	v_pk_fma_f32 v[168:169], v[164:165], v[168:169], v[76:77] op_sel:[0,1,0] op_sel_hi:[1,0,1] neg_lo:[1,0,0]
	s_nop 0
	v_cvt_pk_bf16_f32 v79, v168, v169
	v_add_u32_e32 v74, 0x2600, v1
	ds_write2_b32 v74, v75, v79 offset0:88 offset1:156
	v_add_u32_e32 v78, 0x1000, v200
	ds_read2_b64 v[70:73], v78 offset0:148 offset1:214
	s_waitcnt lgkmcnt(2)
; #define LAS __attribute__((address_space(3)))
; __device__ __forceinline__ float gelu_tanh(float x) { const float z = 0.7978845608028654f * (x + 0.044715f * x * x * x); return x * __builtin_amdgcn_rcpf(1.0f + __expf(-2.0f * z)); }
; #define LDS_WAIT() asm volatile("s_waitcnt lgkmcnt(0)" ::: "memory")
; __device__ __forceinline__ void s5_scan2(LAS unsigned char* lds, const S5Params& P, const bf16_t* U, const float* ES, bf16_t* Gb, int bid, int G) {
;     ...
;             for (int i = 0; i < 16; ++i) { const f32x2 bu = *(const LAS f32x2*)(wlds + i * S5_BU_STRIDE + lane * 8);
;                 const float nre = L.abr * sre - L.abi * sim + bu[0], nim = L.abr * sim + L.abi * sre + bu[1]; sre = nre; sim = nim;
;                 *(LAS unsigned*)(sb + i * S5_SB_STRIDE + lane * 4) = cvt_pk_bf16(sre, sim); }
;             LDS_WAIT(); __builtin_amdgcn_wave_barrier();
;             f32x4 y = (f32x4){0.f, 0.f, 0.f, 0.f};
; #pragma unroll
;             for (int ks = 0; ks < 4; ++ks) { const bf16x8 sf = *(const LAS bf16x8*)(sb + fr * S5_SB_STRIDE + ks * 64 + fq * 16);
;                 y = __builtin_amdgcn_mfma_f32_16x16x32_bf16(cf[ks], sf, y, 0, 0, 0); }
;             const f32x4 uu = *(const LAS f32x4*)(ut + fr * 16 + fq * 4);
;             u32x2 w; w.x = cvt_pk_bf16(gelu_tanh(y[0] + dsk[0] * uu[0]), gelu_tanh(y[1] + dsk[1] * uu[1])); w.y = cvt_pk_bf16(gelu_tanh(y[2] + dsk[2] * uu[2]), gelu_tanh(y[3] + dsk[3] * uu[3]));
;             *(u32x2*)(Gb + (size_t)(t0 + fr) * D + g * 16 + fq * 4) = w;
;             LDS_WAIT(); __builtin_amdgcn_wave_barrier();
	v_pk_fma_f32 v[76:77], v[166:167], v[168:169], v[66:67]
	s_nop 0
	v_pk_fma_f32 v[168:169], v[164:165], v[168:169], v[76:77] op_sel:[0,1,0] op_sel_hi:[1,0,1] neg_lo:[1,0,0]
	s_nop 0
	v_cvt_pk_bf16_f32 v75, v168, v169
	v_pk_fma_f32 v[76:77], v[166:167], v[168:169], v[68:69]
	s_nop 0
	v_pk_fma_f32 v[168:169], v[164:165], v[168:169], v[76:77] op_sel:[0,1,0] op_sel_hi:[1,0,1] neg_lo:[1,0,0]
	s_nop 0
	v_cvt_pk_bf16_f32 v79, v168, v169
	v_add_u32_e32 v74, 0x2800, v1
	ds_write2_b32 v74, v75, v79 offset0:96 offset1:164
	v_add_u32_e32 v78, 0x1800, v200
	ds_read2_b64 v[66:69], v78 offset0:24 offset1:90
	s_waitcnt lgkmcnt(2)
	v_pk_fma_f32 v[76:77], v[166:167], v[168:169], v[70:71]
	s_nop 0
	v_pk_fma_f32 v[168:169], v[164:165], v[168:169], v[76:77] op_sel:[0,1,0] op_sel_hi:[1,0,1] neg_lo:[1,0,0]
	s_nop 0
	v_cvt_pk_bf16_f32 v75, v168, v169
	v_pk_fma_f32 v[76:77], v[166:167], v[168:169], v[72:73]
	s_nop 0
	v_pk_fma_f32 v[168:169], v[164:165], v[168:169], v[76:77] op_sel:[0,1,0] op_sel_hi:[1,0,1] neg_lo:[1,0,0]
	s_nop 0
	v_cvt_pk_bf16_f32 v79, v168, v169
	v_add_u32_e32 v74, 0x2a00, v1
	ds_write2_b32 v74, v75, v79 offset0:104 offset1:172
	v_add_u32_e32 v78, 0x1800, v200
	ds_read2_b64 v[70:73], v78 offset0:156 offset1:222
	s_waitcnt lgkmcnt(2)
	v_pk_fma_f32 v[76:77], v[166:167], v[168:169], v[66:67]
	s_nop 0
	v_pk_fma_f32 v[168:169], v[164:165], v[168:169], v[76:77] op_sel:[0,1,0] op_sel_hi:[1,0,1] neg_lo:[1,0,0]
	s_nop 0
	v_cvt_pk_bf16_f32 v75, v168, v169
	v_pk_fma_f32 v[76:77], v[166:167], v[168:169], v[68:69]
	s_nop 0
	v_pk_fma_f32 v[168:169], v[164:165], v[168:169], v[76:77] op_sel:[0,1,0] op_sel_hi:[1,0,1] neg_lo:[1,0,0]
	s_nop 0
	v_cvt_pk_bf16_f32 v79, v168, v169
	v_add_u32_e32 v74, 0x2c00, v1
	ds_write2_b32 v74, v75, v79 offset0:112 offset1:180
	s_waitcnt lgkmcnt(1)
	v_pk_fma_f32 v[76:77], v[166:167], v[168:169], v[70:71]
	s_nop 0
	v_pk_fma_f32 v[168:169], v[164:165], v[168:169], v[76:77] op_sel:[0,1,0] op_sel_hi:[1,0,1] neg_lo:[1,0,0]
	s_nop 0
	v_cvt_pk_bf16_f32 v75, v168, v169
	v_pk_fma_f32 v[76:77], v[166:167], v[168:169], v[72:73]
	s_nop 0
	v_pk_fma_f32 v[168:169], v[164:165], v[168:169], v[76:77] op_sel:[0,1,0] op_sel_hi:[1,0,1] neg_lo:[1,0,0]
	s_nop 0
	v_cvt_pk_bf16_f32 v79, v168, v169
	v_add_u32_e32 v74, 0x2e00, v1
	ds_write2_b32 v74, v75, v79 offset0:120 offset1:188
	s_waitcnt lgkmcnt(0)
	ds_read_b128 v[66:69], v198 offset:8448
	ds_read_b128 v[70:73], v198 offset:8512
	ds_read_b128 v[222:225], v198 offset:8576
	ds_read_b128 v[226:229], v198 offset:8640
	ds_read_b128 v[230:233], v199 offset:12800
	s_waitcnt lgkmcnt(4)
	v_mfma_f32_16x16x32_bf16 v[66:69], v[38:41], v[66:69], 0
	s_waitcnt lgkmcnt(3)
	v_mfma_f32_16x16x32_bf16 v[66:69], v[42:45], v[70:73], v[66:69]
	s_waitcnt lgkmcnt(2)
	v_mfma_f32_16x16x32_bf16 v[66:69], v[46:49], v[222:225], v[66:69]
	s_waitcnt lgkmcnt(1)
	v_mfma_f32_16x16x32_bf16 v[66:69], v[50:53], v[226:229], v[66:69]
	s_waitcnt vmcnt(1) lgkmcnt(0)
	s_nop 5
	v_pk_fma_f32 v[66:67], v[30:31], v[230:231], v[66:67]
	v_pk_fma_f32 v[68:69], v[32:33], v[232:233], v[68:69]
	v_mul_f32_e32 v1, 0x3d372713, v66
	v_mul_f32_e32 v1, v66, v1
	v_fma_f32 v1, v66, v1, v66
	v_mul_f32_e32 v1, 0x3f4c422a, v1
	v_mul_f32_e32 v1, -2.0, v1
	v_mul_f32_e32 v1, 0x3fb8aa3b, v1
	v_exp_f32_e32 v1, v1
	s_nop 0
	v_add_f32_e32 v1, 1.0, v1
	v_rcp_f32_e32 v70, v1
	v_mul_f32_e32 v1, 0x3d372713, v67
	v_mul_f32_e32 v1, v67, v1
	v_fma_f32 v1, v67, v1, v67
	v_mul_f32_e32 v1, 0x3f4c422a, v1
	v_mul_f32_e32 v1, -2.0, v1
	v_mul_f32_e32 v1, 0x3fb8aa3b, v1
	v_exp_f32_e32 v1, v1
	s_nop 0
	v_add_f32_e32 v1, 1.0, v1
	v_rcp_f32_e32 v71, v1
	v_mul_f32_e32 v1, 0x3d372713, v68
	v_mul_f32_e32 v1, v68, v1
	v_fma_f32 v1, v68, v1, v68
	v_mul_f32_e32 v1, 0x3f4c422a, v1
	v_mul_f32_e32 v1, -2.0, v1
	v_mul_f32_e32 v1, 0x3fb8aa3b, v1
	v_exp_f32_e32 v1, v1
	v_pk_mul_f32 v[66:67], v[66:67], v[70:71]
	v_add_f32_e32 v1, 1.0, v1
	v_rcp_f32_e32 v70, v1
	v_mul_f32_e32 v1, 0x3d372713, v69
	v_mul_f32_e32 v1, v69, v1
	v_fma_f32 v1, v69, v1, v69
	v_mul_f32_e32 v1, 0x3f4c422a, v1
	v_mul_f32_e32 v1, -2.0, v1
	v_mul_f32_e32 v1, 0x3fb8aa3b, v1
	v_exp_f32_e32 v1, v1
	v_cvt_pk_bf16_f32 v66, v66, v67
	v_add_f32_e32 v1, 1.0, v1
	v_rcp_f32_e32 v71, v1
	s_nop 0
	v_pk_mul_f32 v[68:69], v[68:69], v[70:71]
	s_nop 0
	v_cvt_pk_bf16_f32 v67, v68, v69
	v_add_u32_e32 v68, s0, v177
	v_ashrrev_i32_e32 v69, 31, v68
	v_lshlrev_b64 v[68:69], 12, v[68:69]
	v_lshl_add_u64 v[68:69], v[58:59], 0, v[68:69]
	global_store_dwordx2 v[68:69], v[66:67], off
	s_waitcnt lgkmcnt(0)
	s_mov_b32 s0, s3
	v_mov_b64_e32 v[66:67], v[64:65]
	s_cbranch_scc0 .LBB0_1251
	s_add_i32 s34, s34, s82
	s_add_i32 s26, s26, s82
	s_cmpk_gt_i32 s34, 0xfff
	s_cbranch_scc0 .LBB0_1235
